# MLA attention: V^T LDS tile re-laid out (stride 272, 8-byte key groups permuted) so each P.V A fragment is one ds_read_b128 instead of ds_read2_b64
# speedup vs baseline: 1.0042x; 1.0042x over previous
; __global__ void __launch_bounds__(512, 2) fwd_mega(Args args) {
;     ...
;         const int vcu = (G % 8 == 0) ? (bx % 8) * (G / 8) + bx / 8 : bx;
;         float kbound;
;         { const float* kng = args.in[18]; float gmx = fabsf(kng[lane]); if (lane < 32) gmx = fmaxf(gmx, fabsf(kng[64 + lane]));
; #pragma unroll
;           for (int o_ = 1; o_ < 64; o_ <<= 1) gmx = fmaxf(gmx, __shfl_xor(gmx, o_));
;           kbound = gmx * 9.797958971f * 1.01f; }
;     ...
;         for (int p = vcu; p < 256; p += G) {
;             const int bh = p >> 4, s = p & 15, b = bh >> 3, hd = bh & 7;
; #pragma unroll 1
;             for (int e = 0; e < 2; ++e) {
;                 const int qb = e == 0 ? 31 - s : s, q0 = qb * 256;
;                 attn_unit<96, 64, true, 128, true>(QRAW + ((size_t)(b * SEQ + q0)) * 768 + hd * 96, 768, KF + (size_t)b * SEQ * 768 + hd * 96, 768, VT + (size_t)(b * 8 + hd) * 64 * SEQ, SEQ,
;                                         YB + ((size_t)(b * SEQ + q0)) * 512 + hd * 64, 512, q0, (q0 + 256) / 128, lds, kbound, args.in[17], positions + b * SEQ + q0, QSCALE_MLA);
.LBB0_1475:
	s_or_b64 exec, exec, s[2:3]
	v_mbcnt_lo_u32_b32 v0, -1, 0
	v_mbcnt_hi_u32_b32 v2, -1, v0
	v_and_b32_e32 v0, 64, v2
	v_add_u32_e32 v3, 64, v0
	v_xor_b32_e32 v0, 1, v2
	v_cmp_lt_i32_e32 vcc, v0, v3
	v_xor_b32_e32 v4, 2, v2
	s_ashr_i32 s6, s96, 31
	v_cndmask_b32_e32 v0, v2, v0, vcc
	v_lshlrev_b32_e32 v0, 2, v0
	ds_bpermute_b32 v0, v0, v1
	v_max_f32_e32 v1, v1, v1
	v_cmp_lt_i32_e32 vcc, v4, v3
	s_lshr_b32 s6, s6, 29
	s_add_i32 s6, s96, s6
	s_waitcnt lgkmcnt(0)
	v_max_f32_e32 v0, v0, v0
	v_max_f32_e32 v0, v1, v0
	v_cndmask_b32_e32 v1, v2, v4, vcc
	v_lshlrev_b32_e32 v1, 2, v1
	ds_bpermute_b32 v1, v1, v0
	v_xor_b32_e32 v4, 4, v2
	v_cmp_lt_i32_e32 vcc, v4, v3
	s_and_b32 s7, s6, -8
	s_ashr_i32 s3, s86, 3
	s_waitcnt lgkmcnt(0)
	v_max_f32_e32 v1, v1, v1
	v_max_f32_e32 v0, v0, v1
	v_cndmask_b32_e32 v1, v2, v4, vcc
	v_lshlrev_b32_e32 v1, 2, v1
	ds_bpermute_b32 v1, v1, v0
	s_sub_i32 s7, s96, s7
	s_mul_i32 s3, s3, s7
	s_ashr_i32 s6, s6, 3
	s_and_b32 s2, s86, 7
	s_waitcnt lgkmcnt(0)
	v_max_f32_e32 v1, v1, v1
	v_max_f32_e32 v0, v0, v1
	v_xor_b32_e32 v1, 8, v2
	v_cmp_lt_i32_e32 vcc, v1, v3
	s_add_i32 s3, s3, s6
	s_cmp_eq_u32 s2, 0
	v_cndmask_b32_e32 v1, v2, v1, vcc
	v_lshlrev_b32_e32 v1, 2, v1
	ds_bpermute_b32 v1, v1, v0
	s_cselect_b32 s33, s3, s96
	s_cmpk_gt_i32 s33, 0xff
	s_waitcnt lgkmcnt(0)
	v_max_f32_e32 v1, v1, v1
	v_max_f32_e32 v0, v0, v1
	v_xor_b32_e32 v1, 16, v2
	v_cmp_lt_i32_e32 vcc, v1, v3
	s_nop 1
	v_cndmask_b32_e32 v1, v2, v1, vcc
	v_lshlrev_b32_e32 v1, 2, v1
	ds_bpermute_b32 v1, v1, v0
	s_waitcnt lgkmcnt(0)
	v_max_f32_e32 v1, v1, v1
	v_max_f32_e32 v0, v0, v1
	v_xor_b32_e32 v1, 32, v2
	v_cmp_lt_i32_e32 vcc, v1, v3
	s_nop 1
	v_cndmask_b32_e32 v1, v2, v1, vcc
	v_lshlrev_b32_e32 v1, 2, v1
	ds_bpermute_b32 v1, v1, v0
	s_cbranch_scc1 .LBB0_1517
	v_readlane_b32 s8, v249, 17
	s_cmp_lg_u64 s[54:55], 0
	v_readlane_b32 s12, v249, 21
	v_readlane_b32 s13, v249, 22
	s_cselect_b64 s[6:7], -1, 0
	v_readlane_b32 s9, v249, 18
	s_cmp_lg_u64 s[12:13], 0
	s_cselect_b64 s[8:9], -1, 0
	s_add_u32 s72, s4, 0xa700000
	s_addc_u32 s73, s5, 0
	s_add_u32 s76, s4, 0xbf00000
	s_addc_u32 s77, s5, 0
	s_waitcnt lgkmcnt(0)
	v_max_f32_e32 v1, v1, v1
	v_max_f32_e32 v0, v0, v0
	s_add_u32 s80, s4, 0xd700000
	v_max_f32_e32 v0, v0, v1
	v_readlane_b32 s10, v249, 19
	v_readlane_b32 s11, v249, 20
	s_addc_u32 s81, s5, 0
	v_mul_f32_e32 v0, 0x411cc471, v0
	v_readlane_b32 s14, v249, 23
	v_readlane_b32 s15, v249, 24
	v_readlane_b32 s16, v249, 25
	v_readlane_b32 s17, v249, 26
	s_add_u32 s82, s4, 0x7300000
	s_mov_b32 s10, 0x6dc9c883
	v_mul_f32_e32 v174, 0x3f8147ae, v0
	s_addc_u32 s83, s5, 0
	s_movk_i32 s88, 0x600
	s_mov_b32 s89, 0x2aaaaaab
	s_movk_i32 s90, 0xffe0
	v_mov_b32_e32 v1, 0
	v_mov_b32_e32 v175, 0x358637bd
	s_mov_b32 s11, 0x3fc45f30
	s_mov_b32 s91, 0xf800000
	v_mov_b32_e32 v176, 0x260
	s_mov_b32 s52, 0x42c80000
	s_movk_i32 s53, 0xd0
	s_movk_i32 s56, 0x110
	s_mov_b32 s57, 0xd000
	s_mov_b32 s58, 0x41000000
	s_mov_b64 s[14:15], 0x100
	s_mov_b64 s[16:17], 0x30000
	v_mov_b32_e32 v177, 0xf149f2ca
	v_readlane_b32 s18, v249, 27
	v_readlane_b32 s19, v249, 28
	v_readlane_b32 s20, v249, 29
	v_readlane_b32 s21, v249, 30
	v_readlane_b32 s22, v249, 31
	v_readlane_b32 s23, v249, 32
	s_branch .LBB0_1478

; #define LAS __attribute__((address_space(3)))
; DI float xhalf_sum(float m) { auto rr = __builtin_amdgcn_permlane32_swap(__float_as_uint(m), __float_as_uint(m), false, false); return __uint_as_float(rr[0]) + __uint_as_float(rr[1]); }
; template <int DQK, int DV, bool CAUSAL, int KT, bool PRIO>
; DI void attn_unit(const bf16_t* Qb, int qpitch, const bf16_t* Kb, int kpitch, const bf16_t* Vtb, int vpitch, bf16_t* Ob, int opitch, int q0, int nt, LAS unsigned char* lds, float kbound, const float* qgain, const int* qpos, float qscale) {
;     ...
;     auto lstore = [&](int buf) {
; #pragma unroll
;         for (int i = 0; i < NKR; ++i) { const int c = tid + i * 512; if (NKC % 512 == 0 || c < NKC) *(LAS u32x4*)(lds + buf * KBUF + (c / KCH) * KS + (c % KCH) * 16) = kreg[i]; }
; #pragma unroll
;         for (int i = 0; i < NVR; ++i) { const int c = tid + i * 512; LAS unsigned char* p = lds + VOFF + buf * VBUF + (c / VCH) * VS + (c % VCH) * 16;
;             *(LAS u32x2*)p = (u32x2){vreg[i].x, vreg[i].y}; *(LAS u32x2*)(p + 8) = (u32x2){vreg[i].z, vreg[i].w}; }
;     };
;     ...
;     if (PRIO) {
;         float q2 = 0.f;
; #pragma unroll
;         for (int ks = 0; ks < DQK / 16; ++ks)
; #pragma unroll
;             for (int e = 0; e < 8; ++e) { const float v = __uint_as_float(((unsigned)(unsigned short)qf[ks][e]) << 16); q2 += v * v; }
;         q2 = xhalf_sum(q2);
;         nomax = __all(sqrtf(q2) * kbound <= 100.0f) != 0;
;     }
;     lstore(0);
;     __syncthreads();
;     const int qabs = q0 + 32 * w + r, qlo = q0 + 32 * w;
.LBB0_1486:
	s_waitcnt vmcnt(0) lgkmcnt(0)
	v_and_b32_e32 v9, 0xffff0000, v116
	v_lshlrev_b32_e32 v8, 16, v116
	v_mul_f32_e32 v11, v9, v9
	v_fmac_f32_e32 v11, v8, v8
	v_lshlrev_b32_e32 v8, 16, v117
	v_fmac_f32_e32 v11, v8, v8
	v_and_b32_e32 v8, 0xffff0000, v117
	v_fmac_f32_e32 v11, v8, v8
	v_lshlrev_b32_e32 v8, 16, v118
	v_fmac_f32_e32 v11, v8, v8
	v_and_b32_e32 v8, 0xffff0000, v118
	v_fmac_f32_e32 v11, v8, v8
	v_lshlrev_b32_e32 v8, 16, v119
	v_fmac_f32_e32 v11, v8, v8
	v_and_b32_e32 v8, 0xffff0000, v119
	v_fmac_f32_e32 v11, v8, v8
	v_lshlrev_b32_e32 v8, 16, v120
	v_fmac_f32_e32 v11, v8, v8
	v_and_b32_e32 v8, 0xffff0000, v120
	v_fmac_f32_e32 v11, v8, v8
	v_lshlrev_b32_e32 v8, 16, v121
	v_fmac_f32_e32 v11, v8, v8
	v_and_b32_e32 v8, 0xffff0000, v121
	v_fmac_f32_e32 v11, v8, v8
	v_lshlrev_b32_e32 v8, 16, v122
	v_fmac_f32_e32 v11, v8, v8
	v_and_b32_e32 v8, 0xffff0000, v122
	v_fmac_f32_e32 v11, v8, v8
	v_lshlrev_b32_e32 v8, 16, v123
	v_fmac_f32_e32 v11, v8, v8
	v_and_b32_e32 v8, 0xffff0000, v123
	v_fmac_f32_e32 v11, v8, v8
	v_lshlrev_b32_e32 v8, 16, v124
	v_fmac_f32_e32 v11, v8, v8
	v_and_b32_e32 v8, 0xffff0000, v124
	v_fmac_f32_e32 v11, v8, v8
	v_lshlrev_b32_e32 v8, 16, v125
	v_fmac_f32_e32 v11, v8, v8
	v_and_b32_e32 v8, 0xffff0000, v125
	v_fmac_f32_e32 v11, v8, v8
	v_lshlrev_b32_e32 v8, 16, v126
	v_fmac_f32_e32 v11, v8, v8
	v_and_b32_e32 v8, 0xffff0000, v126
	v_fmac_f32_e32 v11, v8, v8
	v_lshlrev_b32_e32 v8, 16, v127
	v_fmac_f32_e32 v11, v8, v8
	v_and_b32_e32 v8, 0xffff0000, v127
	v_fmac_f32_e32 v11, v8, v8
	v_lshlrev_b32_e32 v8, 16, v128
	v_fmac_f32_e32 v11, v8, v8
	v_and_b32_e32 v8, 0xffff0000, v128
	v_fmac_f32_e32 v11, v8, v8
	v_lshlrev_b32_e32 v8, 16, v129
	v_fmac_f32_e32 v11, v8, v8
	v_and_b32_e32 v8, 0xffff0000, v129
	v_fmac_f32_e32 v11, v8, v8
	v_lshlrev_b32_e32 v8, 16, v130
	v_fmac_f32_e32 v11, v8, v8
	v_and_b32_e32 v8, 0xffff0000, v130
	v_fmac_f32_e32 v11, v8, v8
	v_lshlrev_b32_e32 v8, 16, v131
	v_fmac_f32_e32 v11, v8, v8
	v_and_b32_e32 v8, 0xffff0000, v131
	v_fmac_f32_e32 v11, v8, v8
	v_lshlrev_b32_e32 v8, 16, v132
	v_fmac_f32_e32 v11, v8, v8
	v_and_b32_e32 v8, 0xffff0000, v132
	v_fmac_f32_e32 v11, v8, v8
	v_lshlrev_b32_e32 v8, 16, v133
	v_fmac_f32_e32 v11, v8, v8
	v_and_b32_e32 v8, 0xffff0000, v133
	v_fmac_f32_e32 v11, v8, v8
	v_lshlrev_b32_e32 v8, 16, v134
	v_fmac_f32_e32 v11, v8, v8
	v_and_b32_e32 v8, 0xffff0000, v134
	v_fmac_f32_e32 v11, v8, v8
	v_lshlrev_b32_e32 v8, 16, v135
	v_fmac_f32_e32 v11, v8, v8
	v_and_b32_e32 v8, 0xffff0000, v135
	v_fmac_f32_e32 v11, v8, v8
	v_lshlrev_b32_e32 v8, 16, v136
	v_fmac_f32_e32 v11, v8, v8
	v_and_b32_e32 v8, 0xffff0000, v136
	v_fmac_f32_e32 v11, v8, v8
	v_and_b32_e32 v9, 0xffff0000, v137
	v_lshlrev_b32_e32 v8, 16, v137
	v_pk_mul_f32 v[8:9], v[8:9], v[8:9]
	s_xor_b64 s[34:35], s[2:3], -1
	v_add_f32_e32 v8, v8, v11
	v_add_f32_e32 v11, v9, v8
	v_and_b32_e32 v9, 0xffff0000, v138
	v_lshlrev_b32_e32 v8, 16, v138
	v_pk_mul_f32 v[8:9], v[8:9], v[8:9]
	v_mad_i64_i32 v[2:3], s[2:3], v149, s88, 0
	v_add_f32_e32 v8, v8, v11
	v_add_f32_e32 v11, v9, v8
	v_and_b32_e32 v9, 0xffff0000, v139
	v_lshlrev_b32_e32 v8, 16, v139
	v_pk_mul_f32 v[8:9], v[8:9], v[8:9]
	v_mad_i64_i32 v[4:5], s[2:3], v151, s88, 0
	v_add_f32_e32 v8, v8, v11
	v_add_f32_e32 v8, v9, v8
	v_mov_b32_e32 v9, v8
	s_nop 1
	v_permlane32_swap_b32_e32 v8, v9
	v_add_f32_e32 v8, v8, v9
	v_mul_f32_e32 v9, 0x4f800000, v8
	v_cmp_gt_f32_e32 vcc, s91, v8
	v_mad_i64_i32 v[6:7], s[2:3], v153, s88, 0
	s_nop 0
	v_cndmask_b32_e32 v8, v8, v9, vcc
	v_sqrt_f32_e32 v9, v8
	s_add_i32 s2, s38, 0x100
	s_lshr_b32 s68, s2, 7
	v_mul_lo_u32 v178, v149, s53
	v_add_u32_e32 v11, -1, v9
	v_fma_f32 v12, -v11, v9, v8
	v_cmp_ge_f32_e64 s[2:3], 0, v12
	v_add_u32_e32 v12, 1, v9
	v_lshlrev_b32_e32 v179, 4, v150
	v_cndmask_b32_e64 v11, v9, v11, s[2:3]
	v_fma_f32 v9, -v12, v9, v8
	v_cmp_lt_f32_e64 s[2:3], 0, v9
	v_mul_lo_u32 v181, v151, s53
	v_lshlrev_b32_e32 v182, 4, v152
	v_cndmask_b32_e64 v9, v11, v12, s[2:3]
	v_mul_f32_e32 v11, 0x37800000, v9
	v_cndmask_b32_e32 v9, v9, v11, vcc
	v_cmp_class_f32_e32 vcc, v8, v176
	v_mul_lo_u32 v183, v153, s53
	v_lshlrev_b32_e32 v184, 4, v154
	v_cndmask_b32_e32 v8, v9, v8, vcc
	v_mul_f32_e32 v8, v174, v8
	v_cmp_ge_f32_e32 vcc, s52, v8
	v_add3_u32 v8, 0, v178, v179
	ds_write_b128 v8, v[96:99]
	v_add3_u32 v8, 0, v181, v182
	ds_write_b128 v8, v[100:103]
	v_add3_u32 v8, 0, v183, v184
	v_mul_lo_u32 v185, v68, s56
	ds_write_b128 v8, v[104:107]
	v_add_u32_e32 v8, 0, v185
	v_and_b32_e32 v186, 1, v69
	v_lshlrev_b32_e32 v186, 3, v186
	v_sub_u32_e32 v186, 0, v186
	v_lshl_add_u32 v186, v69, 4, v186
	v_add3_u32 v8, v8, v186, s57
	v_mul_lo_u32 v187, v74, s56
	ds_write2_b64 v8, v[108:109], v[110:111] offset1:2
	v_add_u32_e32 v8, 0, v187
	v_and_b32_e32 v188, 1, v75
	v_lshlrev_b32_e32 v188, 3, v188
	v_sub_u32_e32 v188, 0, v188
	v_lshl_add_u32 v188, v75, 4, v188
	v_and_b32_e32 v10, 31, v155
	v_add3_u32 v8, v8, v188, s57
	s_ashr_i32 s27, s26, 31
	s_and_b32 s69, s39, 0xffffffe0
	ds_write2_b64 v8, v[112:113], v[114:115] offset1:2
	v_mul_u32_u24_e32 v8, 0x110, v10
	s_cmp_lg_u64 vcc, exec
	v_add3_u32 v191, v0, v8, v0
	v_lshl_add_u64 v[8:9], s[22:23], 0, v[70:71]
	s_cselect_b64 s[2:3], -1, 0
	s_add_i32 s69, s69, s38
	v_lshl_add_u64 v[164:165], v[72:73], 1, v[8:9]
	v_lshl_add_u64 v[8:9], s[22:23], 0, v[64:65]
	v_lshl_add_u64 v[6:7], s[24:25], 0, v[6:7]
	v_lshl_add_u64 v[4:5], s[24:25], 0, v[4:5]
	v_lshl_add_u64 v[2:3], s[24:25], 0, v[2:3]
	v_mov_b32_e32 v14, v1
	v_mov_b32_e32 v15, v1
	v_or_b32_e32 v189, s69, v10
	v_mul_u32_u24_e32 v192, 0xd0, v10
	v_lshl_add_u64 v[166:167], v[66:67], 1, v[8:9]
	v_lshl_add_u64 v[168:169], v[62:63], 1, v[6:7]
	v_lshl_add_u64 v[170:171], v[60:61], 1, v[4:5]
	v_lshl_add_u64 v[172:173], v[58:59], 1, v[2:3]
	v_mov_b32_e32 v0, v1
	v_mov_b32_e32 v2, v1
	v_mov_b32_e32 v3, v1
	v_mov_b32_e32 v4, v1
	v_mov_b32_e32 v5, v1
	v_mov_b32_e32 v6, v1
	v_mov_b32_e32 v7, v1
	v_mov_b32_e32 v8, v1
	v_mov_b32_e32 v9, v1
	v_mov_b32_e32 v10, v1
	v_mov_b32_e32 v11, v1
	v_mov_b32_e32 v12, v1
	v_mov_b32_e32 v13, v1
	v_mov_b64_e32 v[30:31], v[14:15]
	v_mov_b64_e32 v[46:47], v[14:15]
	v_mov_b64_e32 v[62:63], v[14:15]
	s_mov_b32 s12, 0
	s_or_b32 s70, s69, 31
	v_lshl_add_u32 v190, v148, 4, 0
	v_lshlrev_b32_e32 v180, 2, v148
	s_mov_b64 s[40:41], -1
	v_mov_b32_e32 v193, 0
	s_mov_b32 s71, 63
	v_mov_b64_e32 v[28:29], v[12:13]
	v_mov_b64_e32 v[26:27], v[10:11]
	v_mov_b64_e32 v[24:25], v[8:9]
	v_mov_b64_e32 v[22:23], v[6:7]
	v_mov_b64_e32 v[20:21], v[4:5]
	v_mov_b64_e32 v[18:19], v[2:3]
	v_mov_b64_e32 v[16:17], v[0:1]
	v_mov_b64_e32 v[44:45], v[12:13]
	v_mov_b64_e32 v[42:43], v[10:11]
	v_mov_b64_e32 v[40:41], v[8:9]
	v_mov_b64_e32 v[38:39], v[6:7]
	v_mov_b64_e32 v[36:37], v[4:5]
	v_mov_b64_e32 v[34:35], v[2:3]
	v_mov_b64_e32 v[32:33], v[0:1]
	v_mov_b64_e32 v[60:61], v[12:13]
	v_mov_b64_e32 v[58:59], v[10:11]
	v_mov_b64_e32 v[56:57], v[8:9]
	v_mov_b64_e32 v[54:55], v[6:7]
	v_mov_b64_e32 v[52:53], v[4:5]
	v_mov_b64_e32 v[50:51], v[2:3]
	v_mov_b64_e32 v[48:49], v[0:1]
	v_mov_b32_e32 v0, 0
	s_waitcnt lgkmcnt(0)
	s_barrier

; #define LAS __attribute__((address_space(3)))
; template <int DQK, int DV, bool CAUSAL, int KT, bool PRIO>
; DI void attn_unit(const bf16_t* Qb, int qpitch, const bf16_t* Kb, int kpitch, const bf16_t* Vtb, int vpitch, bf16_t* Ob, int opitch, int q0, int nt, LAS unsigned char* lds, float kbound, const float* qgain, const int* qpos, float qscale) {
;     ...
;     for (int kt = 0; kt < nt; ++kt) {
;         const int buf = kt & 1;
;         if (kt + 1 < nt) gload(kt + 1);
; #pragma unroll
;         for (int hf = 0; hf < KT / 64; ++hf) {
;             const int key0 = kt * KT + 64 * hf;
;             if (!CAUSAL || key0 <= qlo + 31) {
;                 if (PRIO) {
;                     constexpr int KSN = DQK / 16, NDB = DV / 32;
;                     f32x16 s0 = negm, s1 = negm;
;                     const LAS unsigned char* kb = lds + buf * KBUF + (64 * hf + r) * KS + h * 16;
;                     const LAS unsigned char* vb = lds + VOFF + buf * VBUF + r * VS + h * 8 + 128 * hf;
.LBB0_1489:
	s_and_b32 s75, s12, 1
	s_mul_i32 s13, s75, 0x6800
	v_add_u32_e32 v2, s13, v190
	s_mul_i32 s13, s75, 0x4400
	s_sub_i32 s12, s71, 63
	v_add_u32_e32 v194, v2, v192
	v_add_u32_e32 v2, s13, v191
	s_cmp_gt_i32 s12, s70
	v_add_u32_e32 v14, 0xd000, v2
	v_add_u32_e32 v15, 0xf200, v2
	s_cbranch_scc0 .LBB0_1495
	s_add_i32 s12, s71, 1
	s_cmp_gt_i32 s12, s70
	s_cbranch_scc0 .Lmla_b1_pre

; #define LAS __attribute__((address_space(3)))
; template <int DQK, int DV, bool CAUSAL, int KT, bool PRIO>
; DI void attn_unit(const bf16_t* Qb, int qpitch, const bf16_t* Kb, int kpitch, const bf16_t* Vtb, int vpitch, bf16_t* Ob, int opitch, int q0, int nt, LAS unsigned char* lds, float kbound, const float* qgain, const int* qpos, float qscale) {
;     ...
;     auto lstore = [&](int buf) {
; #pragma unroll
;         for (int i = 0; i < NKR; ++i) { const int c = tid + i * 512; if (NKC % 512 == 0 || c < NKC) *(LAS u32x4*)(lds + buf * KBUF + (c / KCH) * KS + (c % KCH) * 16) = kreg[i]; }
; #pragma unroll
;         for (int i = 0; i < NVR; ++i) { const int c = tid + i * 512; LAS unsigned char* p = lds + VOFF + buf * VBUF + (c / VCH) * VS + (c % VCH) * 16;
;             *(LAS u32x2*)p = (u32x2){vreg[i].x, vreg[i].y}; *(LAS u32x2*)(p + 8) = (u32x2){vreg[i].z, vreg[i].w}; }
;     };
;     ...
;         if (kt + 1 < nt) lstore(buf ^ 1);
.LBB0_1492:
	s_xor_b32 s12, s75, 1
	s_mul_i32 s13, s12, 0x6800
	s_add_i32 s13, s13, 0
	v_add3_u32 v2, s13, v178, v179
	s_waitcnt vmcnt(0) lgkmcnt(0)
	ds_write_b128 v2, v[96:99]
	v_add3_u32 v2, s13, v181, v182
	s_mulk_i32 s12, 0xdc00
	ds_write_b128 v2, v[100:103]
	v_add3_u32 v2, s13, v183, v184
	s_add_i32 s13, s13, s12
	ds_write_b128 v2, v[104:107]
	v_add_u32_e32 v2, s13, v185
	v_add3_u32 v2, v2, v186, s57
	ds_write2_b64 v2, v[108:109], v[110:111] offset1:2
	v_add_u32_e32 v2, s13, v187
	v_add3_u32 v2, v2, v188, s57
	ds_write2_b64 v2, v[112:113], v[114:115] offset1:2

; #define LAS __attribute__((address_space(3)))
; #define MFMA32(a, b, c) __builtin_amdgcn_mfma_f32_32x32x16_bf16((a), (b), (c), 0, 0, 0)
; template <int DQK, int DV, bool CAUSAL, int KT, bool PRIO>
; DI void attn_unit(const bf16_t* Qb, int qpitch, const bf16_t* Kb, int kpitch, const bf16_t* Vtb, int vpitch, bf16_t* Ob, int opitch, int q0, int nt, LAS unsigned char* lds, float kbound, const float* qgain, const int* qpos, float qscale) {
;     ...
;             const int key0 = kt * KT + 64 * hf;
;             if (!CAUSAL || key0 <= qlo + 31) {
;                 if (PRIO) {
;                     constexpr int KSN = DQK / 16, NDB = DV / 32;
;                     f32x16 s0 = negm, s1 = negm;
;                     const LAS unsigned char* kb = lds + buf * KBUF + (64 * hf + r) * KS + h * 16;
;                     const LAS unsigned char* vb = lds + VOFF + buf * VBUF + r * VS + h * 8 + 128 * hf;
;                     bf16x8 kf0[KSN], kf1[KSN], vf[4][NDB];
; #pragma unroll
;                     for (int ks = 0; ks < KSN; ++ks) { kf0[ks] = *(const LAS bf16x8*)(kb + ks * 32); kf1[ks] = *(const LAS bf16x8*)(kb + 32 * KS + ks * 32); }
;                     __builtin_amdgcn_sched_barrier(0); __builtin_amdgcn_s_setprio(1); __builtin_amdgcn_sched_barrier(0);
; #pragma unroll
;                     for (int ks = 0; ks < KSN; ++ks) { s0 = MFMA32(kf0[ks], qf[ks], s0); s1 = MFMA32(kf1[ks], qf[ks], s1); }
;                     __builtin_amdgcn_sched_barrier(0); __builtin_amdgcn_s_setprio(0); __builtin_amdgcn_sched_barrier(0);
; #pragma unroll
;                     for (int q4 = 0; q4 < 4; ++q4)
; #pragma unroll
;                         for (int d = 0; d < NDB; ++d) { const LAS unsigned char* vp = vb + d * 32 * VS + q4 * 32;
;                             const s16x4 lo = *(const LAS s16x4*)vp, hi = *(const LAS s16x4*)(vp + 16); vf[q4][d] = (bf16x8){lo[0], lo[1], lo[2], lo[3], hi[0], hi[1], hi[2], hi[3]}; }
;                     if (CAUSAL && key0 + 63 > qlo) {
; #pragma unroll
;                         for (int i = 0; i < 16; ++i) { const int key = key0 + (i & 3) + 8 * (i >> 2) + 4 * h; if (key > qabs) s0[i] = -1e30f; if (key + 32 > qabs) s1[i] = -1e30f; }
.LBB0_1495:
	ds_read_b128 v[2:5], v194
	ds_read_b128 v[6:9], v194 offset:32
	ds_read_b128 v[10:13], v194 offset:6656
	ds_read_b128 v[140:143], v194 offset:6688
	ds_read_b128 v[144:147], v194 offset:64
	ds_read_b128 v[148:151], v194 offset:96
	ds_read_b128 v[152:155], v194 offset:6720
	ds_read_b128 v[156:159], v194 offset:6752
	ds_read_b128 v[198:201], v194 offset:128
	ds_read_b128 v[202:205], v194 offset:160
	ds_read_b128 v[206:209], v194 offset:6784
	ds_read_b128 v[210:213], v194 offset:6816
	s_setprio 1
	s_setprio 0
	s_waitcnt lgkmcnt(0)
	v_mfma_f32_32x32x16_bf16 v[80:95], v[2:5], v[116:119], v[48:63]
	s_cmp_le_i32 s71, s69
	v_mfma_f32_32x32x16_bf16 v[64:79], v[10:13], v[116:119], v[48:63]
	v_mfma_f32_32x32x16_bf16 v[80:95], v[6:9], v[120:123], v[80:95]
	v_mfma_f32_32x32x16_bf16 v[64:79], v[140:143], v[120:123], v[64:79]
	v_mfma_f32_32x32x16_bf16 v[80:95], v[144:147], v[124:127], v[80:95]
	v_mfma_f32_32x32x16_bf16 v[64:79], v[152:155], v[124:127], v[64:79]
	ds_read_b128 v[152:155], v14
	ds_read_b128 v[140:143], v14 offset:32
	v_mfma_f32_32x32x16_bf16 v[80:95], v[148:151], v[128:131], v[80:95]
	v_mfma_f32_32x32x16_bf16 v[64:79], v[156:159], v[128:131], v[64:79]
	ds_read_b128 v[156:159], v15
	ds_read_b128 v[148:151], v15 offset:32
	ds_read_b128 v[144:147], v14 offset:64
	ds_read_b128 v[10:13], v15 offset:64
	ds_read_b128 v[6:9], v14 offset:96
	ds_read_b128 v[2:5], v15 offset:96
	v_mfma_f32_32x32x16_bf16 v[80:95], v[198:201], v[132:135], v[80:95]
	v_mfma_f32_32x32x16_bf16 v[64:79], v[206:209], v[132:135], v[64:79]
	v_mfma_f32_32x32x16_bf16 v[80:95], v[202:205], v[136:139], v[80:95]
	v_mfma_f32_32x32x16_bf16 v[64:79], v[210:213], v[136:139], v[64:79]
	ds_read_b128 v[214:217], v194 offset:13312
	ds_read_b128 v[218:221], v194 offset:13344
	ds_read_b128 v[222:225], v194 offset:19968
	ds_read_b128 v[226:229], v194 offset:20000
	ds_read_b128 v[230:233], v194 offset:13376
	ds_read_b128 v[234:237], v194 offset:13408
	ds_read_b128 v[238:241], v194 offset:20032
	ds_read_b128 v[242:245], v194 offset:20064
	s_cbranch_scc1 .LBB0_1497
	v_add_u32_e32 v195, s71, v180
	v_subrev_u32_e32 v198, 31, v195
	v_subrev_u32_e32 v197, 63, v195
	v_cmp_le_i32_e32 vcc, v198, v189
	s_nop 6
	v_cndmask_b32_e32 v64, v177, v64, vcc
	v_cmp_lt_i32_e32 vcc, v197, v189
	s_nop 1
	v_cndmask_b32_e32 v81, v177, v81, vcc
	v_cmp_le_i32_e32 vcc, v197, v189
	v_subrev_u32_e32 v197, 30, v195
	s_nop 0
	v_cndmask_b32_e32 v80, v177, v80, vcc
	v_cmp_le_i32_e32 vcc, v197, v189
	v_subrev_u32_e32 v197, 61, v195
	s_nop 0
	v_cndmask_b32_e32 v65, v177, v65, vcc
	v_cmp_le_i32_e32 vcc, v197, v189
	v_subrev_u32_e32 v197, 29, v195
	s_nop 0
	v_cndmask_b32_e32 v82, v177, v82, vcc
	v_cmp_le_i32_e32 vcc, v197, v189
	v_subrev_u32_e32 v197, 60, v195
	s_nop 0
	v_cndmask_b32_e32 v66, v177, v66, vcc
	v_cmp_le_i32_e32 vcc, v197, v189
	v_subrev_u32_e32 v197, 28, v195
	s_nop 0
	v_cndmask_b32_e32 v83, v177, v83, vcc
	v_cmp_le_i32_e32 vcc, v197, v189
	v_subrev_u32_e32 v197, 55, v195
	s_nop 0
	v_cndmask_b32_e32 v67, v177, v67, vcc
	v_cmp_le_i32_e32 vcc, v197, v189
	v_subrev_u32_e32 v197, 23, v195
	s_nop 0
	v_cndmask_b32_e32 v84, v177, v84, vcc
	v_cmp_le_i32_e32 vcc, v197, v189
	v_subrev_u32_e32 v197, 54, v195
	s_nop 0
	v_cndmask_b32_e32 v68, v177, v68, vcc
	v_cmp_le_i32_e32 vcc, v197, v189
	v_subrev_u32_e32 v197, 22, v195
	s_nop 0
	v_cndmask_b32_e32 v85, v177, v85, vcc
	v_cmp_le_i32_e32 vcc, v197, v189
	v_subrev_u32_e32 v197, 53, v195
	s_nop 0
	v_cndmask_b32_e32 v69, v177, v69, vcc
	v_cmp_le_i32_e32 vcc, v197, v189
	v_subrev_u32_e32 v197, 21, v195
	s_nop 0
	v_cndmask_b32_e32 v86, v177, v86, vcc
	v_cmp_le_i32_e32 vcc, v197, v189
	v_subrev_u32_e32 v197, 52, v195
	s_nop 0
	v_cndmask_b32_e32 v70, v177, v70, vcc
	v_cmp_le_i32_e32 vcc, v197, v189
	v_subrev_u32_e32 v197, 20, v195
	s_nop 0
	v_cndmask_b32_e32 v87, v177, v87, vcc
	v_cmp_le_i32_e32 vcc, v197, v189
	v_subrev_u32_e32 v197, 47, v195
	s_nop 0
	v_cndmask_b32_e32 v71, v177, v71, vcc
	v_cmp_le_i32_e32 vcc, v197, v189
	v_add_u32_e32 v197, -15, v195
	s_nop 0
	v_cndmask_b32_e32 v88, v177, v88, vcc
	v_cmp_le_i32_e32 vcc, v197, v189
	v_subrev_u32_e32 v197, 46, v195
	s_nop 0
	v_cndmask_b32_e32 v72, v177, v72, vcc
	v_cmp_le_i32_e32 vcc, v197, v189
	v_add_u32_e32 v197, -14, v195
	s_nop 0
	v_cndmask_b32_e32 v89, v177, v89, vcc
	v_cmp_le_i32_e32 vcc, v197, v189
	v_subrev_u32_e32 v197, 45, v195
	s_nop 0
	v_cndmask_b32_e32 v73, v177, v73, vcc
	v_cmp_le_i32_e32 vcc, v197, v189
	v_add_u32_e32 v197, -13, v195
	s_nop 0
	v_cndmask_b32_e32 v90, v177, v90, vcc
	v_cmp_le_i32_e32 vcc, v197, v189
	v_subrev_u32_e32 v197, 44, v195
	s_nop 0
	v_cndmask_b32_e32 v74, v177, v74, vcc
	v_cmp_le_i32_e32 vcc, v197, v189
	v_add_u32_e32 v197, -12, v195
	s_nop 0
	v_cndmask_b32_e32 v91, v177, v91, vcc
	v_cmp_le_i32_e32 vcc, v197, v189
	v_subrev_u32_e32 v197, 39, v195
	s_nop 0
	v_cndmask_b32_e32 v75, v177, v75, vcc
	v_cmp_le_i32_e32 vcc, v197, v189
	v_add_u32_e32 v197, -7, v195
	s_nop 0
	v_cndmask_b32_e32 v92, v177, v92, vcc
	v_cmp_le_i32_e32 vcc, v197, v189
	v_subrev_u32_e32 v197, 38, v195
	s_nop 0
	v_cndmask_b32_e32 v76, v177, v76, vcc
	v_cmp_le_i32_e32 vcc, v197, v189
	v_add_u32_e32 v197, -6, v195
	s_nop 0
	v_cndmask_b32_e32 v93, v177, v93, vcc
	v_cmp_le_i32_e32 vcc, v197, v189
	v_subrev_u32_e32 v197, 37, v195
	s_nop 0
	v_cndmask_b32_e32 v77, v177, v77, vcc
	v_cmp_le_i32_e32 vcc, v197, v189
	v_add_u32_e32 v197, -5, v195
	s_nop 0
	v_cndmask_b32_e32 v94, v177, v94, vcc
	v_cmp_le_i32_e32 vcc, v197, v189
	v_subrev_u32_e32 v197, 36, v195
	v_add_u32_e32 v195, -4, v195
	v_cndmask_b32_e32 v78, v177, v78, vcc
	v_cmp_le_i32_e32 vcc, v197, v189
	s_nop 1
	v_cndmask_b32_e32 v95, v177, v95, vcc
	v_cmp_le_i32_e32 vcc, v195, v189
	s_nop 1
	v_cndmask_b32_e32 v79, v177, v79, vcc

; #define LAS __attribute__((address_space(3)))
; #define MFMA32(a, b, c) __builtin_amdgcn_mfma_f32_32x32x16_bf16((a), (b), (c), 0, 0, 0)
; template <int DQK, int DV, bool CAUSAL, int KT, bool PRIO>
; DI void attn_unit(const bf16_t* Qb, int qpitch, const bf16_t* Kb, int kpitch, const bf16_t* Vtb, int vpitch, bf16_t* Ob, int opitch, int q0, int nt, LAS unsigned char* lds, float kbound, const float* qgain, const int* qpos, float qscale) {
;     ...
;             const int key0 = kt * KT + 64 * hf;
;             if (!CAUSAL || key0 <= qlo + 31) {
;                 if (PRIO) {
;                     constexpr int KSN = DQK / 16, NDB = DV / 32;
;                     f32x16 s0 = negm, s1 = negm;
;                     const LAS unsigned char* kb = lds + buf * KBUF + (64 * hf + r) * KS + h * 16;
;                     const LAS unsigned char* vb = lds + VOFF + buf * VBUF + r * VS + h * 8 + 128 * hf;
;                     bf16x8 kf0[KSN], kf1[KSN], vf[4][NDB];
; #pragma unroll
;                     for (int ks = 0; ks < KSN; ++ks) { kf0[ks] = *(const LAS bf16x8*)(kb + ks * 32); kf1[ks] = *(const LAS bf16x8*)(kb + 32 * KS + ks * 32); }
;                     __builtin_amdgcn_sched_barrier(0); __builtin_amdgcn_s_setprio(1); __builtin_amdgcn_sched_barrier(0);
; #pragma unroll
;                     for (int ks = 0; ks < KSN; ++ks) { s0 = MFMA32(kf0[ks], qf[ks], s0); s1 = MFMA32(kf1[ks], qf[ks], s1); }
;                     __builtin_amdgcn_sched_barrier(0); __builtin_amdgcn_s_setprio(0); __builtin_amdgcn_sched_barrier(0);
; #pragma unroll
;                     for (int q4 = 0; q4 < 4; ++q4)
; #pragma unroll
;                         for (int d = 0; d < NDB; ++d) { const LAS unsigned char* vp = vb + d * 32 * VS + q4 * 32;
;                             const s16x4 lo = *(const LAS s16x4*)vp, hi = *(const LAS s16x4*)(vp + 16); vf[q4][d] = (bf16x8){lo[0], lo[1], lo[2], lo[3], hi[0], hi[1], hi[2], hi[3]}; }
;                     if (CAUSAL && key0 + 63 > qlo) {
; #pragma unroll
;                         for (int i = 0; i < 16; ++i) { const int key = key0 + (i & 3) + 8 * (i >> 2) + 4 * h; if (key > qabs) s0[i] = -1e30f; if (key + 32 > qabs) s1[i] = -1e30f; }
.LBB0_1505:
	ds_read_b128 v[198:201], v194 offset:13440
	ds_read_b128 v[202:205], v194 offset:13472
	ds_read_b128 v[206:209], v194 offset:20096
	ds_read_b128 v[210:213], v194 offset:20128
	s_setprio 1
	s_setprio 0
	s_waitcnt lgkmcnt(4)
	v_mfma_f32_32x32x16_bf16 v[80:95], v[214:217], v[116:119], v[48:63]
	s_add_i32 s12, s71, 64
	s_cmp_le_i32 s12, s69
	v_mfma_f32_32x32x16_bf16 v[64:79], v[222:225], v[116:119], v[48:63]
	v_mfma_f32_32x32x16_bf16 v[80:95], v[218:221], v[120:123], v[80:95]
	v_mfma_f32_32x32x16_bf16 v[64:79], v[226:229], v[120:123], v[64:79]
	v_mfma_f32_32x32x16_bf16 v[80:95], v[230:233], v[124:127], v[80:95]
	v_mfma_f32_32x32x16_bf16 v[64:79], v[238:241], v[124:127], v[64:79]
	v_mfma_f32_32x32x16_bf16 v[80:95], v[234:237], v[128:131], v[80:95]
	v_mfma_f32_32x32x16_bf16 v[64:79], v[242:245], v[128:131], v[64:79]
	ds_read_b128 v[156:159], v14 offset:128
	ds_read_b128 v[140:143], v14 offset:160
	ds_read_b128 v[152:155], v15 offset:128
	ds_read_b128 v[148:151], v15 offset:160
	ds_read_b128 v[144:147], v14 offset:192
	ds_read_b128 v[10:13], v15 offset:192
	ds_read_b128 v[6:9], v14 offset:224
	ds_read_b128 v[2:5], v15 offset:224
	s_waitcnt lgkmcnt(8)
	v_mfma_f32_32x32x16_bf16 v[80:95], v[198:201], v[132:135], v[80:95]
	v_mfma_f32_32x32x16_bf16 v[64:79], v[206:209], v[132:135], v[64:79]
	v_mfma_f32_32x32x16_bf16 v[80:95], v[202:205], v[136:139], v[80:95]
	v_mfma_f32_32x32x16_bf16 v[64:79], v[210:213], v[136:139], v[64:79]
	s_cbranch_scc1 .LBB0_1507
	v_add_u32_e32 v14, s71, v180
	v_add_u32_e32 v194, 33, v14
	v_add_u32_e32 v15, 1, v14
	v_cmp_le_i32_e32 vcc, v194, v189
	s_nop 6
	v_cndmask_b32_e32 v64, v177, v64, vcc
	v_cmp_lt_i32_e32 vcc, v15, v189
	s_nop 1
	v_cndmask_b32_e32 v81, v177, v81, vcc
	v_cmp_le_i32_e32 vcc, v15, v189
	v_add_u32_e32 v15, 34, v14
	s_nop 0
	v_cndmask_b32_e32 v80, v177, v80, vcc
	v_cmp_le_i32_e32 vcc, v15, v189
	v_add_u32_e32 v15, 3, v14
	s_nop 0
	v_cndmask_b32_e32 v65, v177, v65, vcc
	v_cmp_le_i32_e32 vcc, v15, v189
	v_add_u32_e32 v15, 35, v14
	s_nop 0
	v_cndmask_b32_e32 v82, v177, v82, vcc
	v_cmp_le_i32_e32 vcc, v15, v189
	v_add_u32_e32 v15, 4, v14
	s_nop 0
	v_cndmask_b32_e32 v66, v177, v66, vcc
	v_cmp_le_i32_e32 vcc, v15, v189
	v_add_u32_e32 v15, 36, v14
	s_nop 0
	v_cndmask_b32_e32 v83, v177, v83, vcc
	v_cmp_le_i32_e32 vcc, v15, v189
	v_add_u32_e32 v15, 9, v14
	s_nop 0
	v_cndmask_b32_e32 v67, v177, v67, vcc
	v_cmp_le_i32_e32 vcc, v15, v189
	v_add_u32_e32 v15, 41, v14
	s_nop 0
	v_cndmask_b32_e32 v84, v177, v84, vcc
	v_cmp_le_i32_e32 vcc, v15, v189
	v_add_u32_e32 v15, 10, v14
	s_nop 0
	v_cndmask_b32_e32 v68, v177, v68, vcc
	v_cmp_le_i32_e32 vcc, v15, v189
	v_add_u32_e32 v15, 42, v14
	s_nop 0
	v_cndmask_b32_e32 v85, v177, v85, vcc
	v_cmp_le_i32_e32 vcc, v15, v189
	v_add_u32_e32 v15, 11, v14
	s_nop 0
	v_cndmask_b32_e32 v69, v177, v69, vcc
	v_cmp_le_i32_e32 vcc, v15, v189
	v_add_u32_e32 v15, 43, v14
	s_nop 0
	v_cndmask_b32_e32 v86, v177, v86, vcc
	v_cmp_le_i32_e32 vcc, v15, v189
	v_add_u32_e32 v15, 12, v14
	s_nop 0
	v_cndmask_b32_e32 v70, v177, v70, vcc
	v_cmp_le_i32_e32 vcc, v15, v189
	v_add_u32_e32 v15, 44, v14
	s_nop 0
	v_cndmask_b32_e32 v87, v177, v87, vcc
	v_cmp_le_i32_e32 vcc, v15, v189
	v_add_u32_e32 v15, 17, v14
	s_nop 0
	v_cndmask_b32_e32 v71, v177, v71, vcc
	v_cmp_le_i32_e32 vcc, v15, v189
	v_add_u32_e32 v15, 49, v14
	s_nop 0
	v_cndmask_b32_e32 v88, v177, v88, vcc
	v_cmp_le_i32_e32 vcc, v15, v189
	v_add_u32_e32 v15, 18, v14
	s_nop 0
	v_cndmask_b32_e32 v72, v177, v72, vcc
	v_cmp_le_i32_e32 vcc, v15, v189
	v_add_u32_e32 v15, 50, v14
	s_nop 0
	v_cndmask_b32_e32 v89, v177, v89, vcc
	v_cmp_le_i32_e32 vcc, v15, v189
	v_add_u32_e32 v15, 19, v14
	s_nop 0
	v_cndmask_b32_e32 v73, v177, v73, vcc
	v_cmp_le_i32_e32 vcc, v15, v189
	v_add_u32_e32 v15, 51, v14
	s_nop 0
	v_cndmask_b32_e32 v90, v177, v90, vcc
	v_cmp_le_i32_e32 vcc, v15, v189
	v_add_u32_e32 v15, 20, v14
	s_nop 0
	v_cndmask_b32_e32 v74, v177, v74, vcc
	v_cmp_le_i32_e32 vcc, v15, v189
	v_add_u32_e32 v15, 52, v14
	s_nop 0
	v_cndmask_b32_e32 v91, v177, v91, vcc
	v_cmp_le_i32_e32 vcc, v15, v189
	v_add_u32_e32 v15, 25, v14
	s_nop 0
	v_cndmask_b32_e32 v75, v177, v75, vcc
	v_cmp_le_i32_e32 vcc, v15, v189
	v_add_u32_e32 v15, 57, v14
	s_nop 0
	v_cndmask_b32_e32 v92, v177, v92, vcc
	v_cmp_le_i32_e32 vcc, v15, v189
	v_add_u32_e32 v15, 26, v14
	s_nop 0
	v_cndmask_b32_e32 v76, v177, v76, vcc
	v_cmp_le_i32_e32 vcc, v15, v189
	v_add_u32_e32 v15, 58, v14
	s_nop 0
	v_cndmask_b32_e32 v93, v177, v93, vcc
	v_cmp_le_i32_e32 vcc, v15, v189
	v_add_u32_e32 v15, 27, v14
	s_nop 0
	v_cndmask_b32_e32 v77, v177, v77, vcc
	v_cmp_le_i32_e32 vcc, v15, v189
	v_add_u32_e32 v15, 59, v14
	s_nop 0
	v_cndmask_b32_e32 v94, v177, v94, vcc
	v_cmp_le_i32_e32 vcc, v15, v189
	v_add_u32_e32 v15, 28, v14
	v_add_u32_e32 v14, 60, v14
	v_cndmask_b32_e32 v78, v177, v78, vcc
	v_cmp_le_i32_e32 vcc, v15, v189
	s_nop 1
	v_cndmask_b32_e32 v95, v177, v95, vcc
	v_cmp_le_i32_e32 vcc, v14, v189
	s_nop 1
	v_cndmask_b32_e32 v79, v177, v79, vcc
